# SSD phase: no raised priority for waves 4-7 (all waves priority 0)
# speedup vs baseline: 1.0032x; 1.0032x over previous
; __device__ __forceinline__ void phase_ssd(const Params& P, int seg, unsigned char* smem) {
;     ...
;     if (__builtin_amdgcn_readfirstlane(tid) >= 256) __builtin_amdgcn_s_setprio(1);
.LBB0_290:
	s_or_b64 exec, exec, s[0:1]
	s_mov_b64 s[0:1], s[80:81]
	v_mov_b32_e32 v5, v172
	s_waitcnt lgkmcnt(0)
	s_barrier
	s_nop 0
	v_readfirstlane_b32 s9, v5
	s_cmpk_gt_i32 s9, 0xff
	s_cbranch_scc0 .LBB0_292
	s_setprio 0
